# 16x16x32 GEMM loop; waves 0-3 issue all LDS-DMA loads of a K-step (own and partner wave's), waves 4-7 none
# speedup vs baseline: 1.0510x; 1.0118x over previous
.LBB0_485:
	s_lshl_b32 s8, s20, 6
	s_mov_b32 s9, 0
	s_lshl_b32 s10, s28, 6
	s_mov_b32 s11, 0
	s_and_b32 s76, s92, 63
	s_mulk_i32 s76, 0xc0
	v_add_u32_e32 v8, s76, v136
	v_ashrrev_i32_e32 v9, 31, v8
	s_lshl_b32 s77, s84, 8
	s_waitcnt vmcnt(3)
	v_mul_lo_u32 v10, s20, v9
	v_mul_lo_u32 v11, s21, v8
	v_mad_u64_u32 v[8:9], s[86:87], s20, v8, 0
	v_add3_u32 v9, v9, v10, v11
	v_add_u32_e32 v10, s77, v136
	v_mad_u64_u32 v[12:13], s[86:87], v10, s28, 0
	v_ashrrev_i32_e32 v11, 31, v10
	s_waitcnt vmcnt(2)
	v_mov_b32_e32 v14, v13
	v_mad_u64_u32 v[14:15], s[86:87], v11, s28, v[14:15]
	v_lshl_add_u64 v[8:9], v[8:9], 1, s[56:57]
	v_mov_b32_e32 v13, v14
	v_readfirstlane_b32 s84, v137
	v_add_u32_e32 v14, 0x2000, v137
	v_lshl_add_u64 v[8:9], v[8:9], 0, v[0:1]
	s_mov_b32 m0, s84
	s_lshl_b64 s[86:87], s[20:21], 7
	v_readfirstlane_b32 s84, v14
	v_add_u32_e32 v14, 0x4000, v137
	global_load_lds_dwordx4 v[8:9], off
	v_lshl_add_u64 v[8:9], v[8:9], 0, s[86:87]
	s_mov_b32 m0, s84
	v_readfirstlane_b32 s84, v14
	v_lshl_add_u64 v[12:13], v[12:13], 1, s[2:3]
	global_load_lds_dwordx4 v[8:9], off
	v_lshl_add_u64 v[8:9], v[8:9], 0, s[86:87]
	s_mov_b32 m0, s84
	s_lshl_b64 s[86:87], s[28:29], 7
	global_load_lds_dwordx4 v[8:9], off
	v_lshl_add_u64 v[8:9], v[12:13], 0, v[0:1]
	v_add_u32_e32 v12, 0x6000, v137
	s_and_b32 s34, s79, 63
	v_readfirstlane_b32 s84, v12
	v_add_u32_e32 v12, 0x8000, v137
	s_mov_b32 m0, s84
	v_readfirstlane_b32 s84, v12
	v_add_u32_e32 v12, 0xa000, v137
	global_load_lds_dwordx4 v[8:9], off
	v_lshl_add_u64 v[8:9], v[8:9], 0, s[86:87]
	s_mov_b32 m0, s84
	v_readfirstlane_b32 s84, v12
	v_add_u32_e32 v12, 0xc000, v137
	global_load_lds_dwordx4 v[8:9], off
	v_lshl_add_u64 v[8:9], v[8:9], 0, s[86:87]
	s_mov_b32 m0, s84
	v_readfirstlane_b32 s84, v12
	global_load_lds_dwordx4 v[8:9], off
	v_lshl_add_u64 v[8:9], v[8:9], 0, s[86:87]
	s_mov_b32 m0, s84
	s_mulk_i32 s34, 0xc0
	global_load_lds_dwordx4 v[8:9], off
	s_mov_b64 s[4:5], 0x80
	v_lshl_add_u64 v[8:9], s[56:57], 0, v[98:99]
	v_add_u32_e32 v2, s34, v136
	v_lshl_add_u64 v[8:9], v[8:9], 0, s[4:5]
	s_lshl_b32 s86, s20, 1
	v_ashrrev_i32_e32 v3, 31, v2
	v_mad_u64_u32 v[100:101], s[56:57], s86, v2, v[8:9]
	v_lshlrev_b64 v[4:5], 1, v[2:3]
	s_mov_b64 s[6:7], 0x100
	s_lshr_b64 s[56:57], s[20:21], 31
	v_lshl_add_u64 v[6:7], v[4:5], 0, s[6:7]
	v_mul_lo_u32 v2, s56, v2
	v_mul_lo_u32 v3, s86, v3
	v_lshl_add_u64 v[4:5], v[4:5], 0, s[4:5]
	v_add3_u32 v101, v2, v101, v3
	v_mul_lo_u32 v2, s20, v7
	v_mul_lo_u32 v3, s21, v6
	v_mad_u64_u32 v[102:103], s[56:57], s20, v6, v[8:9]
	v_add3_u32 v103, v3, v103, v2
	v_mul_lo_u32 v2, s20, v5
	v_mul_lo_u32 v3, s21, v4
	v_mad_u64_u32 v[104:105], s[20:21], s20, v4, v[8:9]
	v_add3_u32 v105, v3, v105, v2
	v_lshl_add_u64 v[2:3], s[2:3], 0, v[98:99]
	v_lshl_add_u64 v[2:3], v[2:3], 0, s[4:5]
	v_lshlrev_b64 v[4:5], 1, v[10:11]
	v_mad_u64_u32 v[106:107], s[2:3], v4, s28, v[2:3]
	v_alignbit_b32 v7, v11, v10, 31
	v_mov_b32_e32 v6, v107
	v_mad_u64_u32 v[6:7], s[2:3], v7, s28, v[6:7]
	v_mov_b32_e32 v107, v6
	v_lshl_add_u64 v[6:7], v[4:5], 0, s[6:7]
	v_mad_u64_u32 v[108:109], s[2:3], v6, s28, v[2:3]
	v_mov_b32_e32 v6, v109
	v_mad_u64_u32 v[6:7], s[2:3], v7, s28, v[6:7]
	s_mov_b64 s[2:3], 0x180
	v_mov_b32_e32 v109, v6
	v_lshl_add_u64 v[6:7], v[4:5], 0, s[2:3]
	v_lshl_add_u64 v[4:5], v[4:5], 0, s[4:5]
	v_mad_u64_u32 v[110:111], s[2:3], v6, s28, v[2:3]
	v_mad_u64_u32 v[112:113], s[2:3], v4, s28, v[2:3]
	v_mov_b32_e32 v6, v111
	v_mov_b32_e32 v2, v113
	s_waitcnt vmcnt(0)
	v_mad_u64_u32 v[6:7], s[2:3], v7, s28, v[6:7]
	v_mad_u64_u32 v[2:3], s[2:3], v5, s28, v[2:3]
	v_mov_b32_e32 v113, v2
	s_lshl_b64 s[2:3], s[28:29], 1
	v_mov_b32_e32 v2, 0
	s_mov_b32 s34, 1
	s_lshr_b32 s84, s28, 6
	v_mov_b32_e32 v111, v6
	s_and_b32 s20, s2, 0xffffff80
	s_mov_b64 s[2:3], 0
	v_mov_b32_e32 v3, v2
	v_mov_b32_e32 v4, v2
	v_mov_b32_e32 v5, v2
	v_mov_b32_e32 v6, v2
	v_mov_b32_e32 v7, v2
	v_mov_b32_e32 v8, v2
	v_mov_b32_e32 v9, v2
	v_mov_b32_e32 v10, v2
	v_mov_b32_e32 v11, v2
	v_mov_b32_e32 v12, v2
	v_mov_b32_e32 v13, v2
	v_mov_b32_e32 v14, v2
	v_mov_b32_e32 v15, v2
	v_mov_b32_e32 v16, v2
	v_mov_b32_e32 v17, v2
	s_waitcnt vmcnt(0)
	v_mov_b32_e32 v18, v2
	v_mov_b32_e32 v19, v2
	v_mov_b32_e32 v20, v2
	v_mov_b32_e32 v21, v2
	v_mov_b32_e32 v22, v2
	v_mov_b32_e32 v23, v2
	v_mov_b32_e32 v24, v2
	v_mov_b32_e32 v25, v2
	v_mov_b32_e32 v26, v2
	v_mov_b32_e32 v27, v2
	v_mov_b32_e32 v28, v2
	v_mov_b32_e32 v29, v2
	v_mov_b32_e32 v30, v2
	v_mov_b32_e32 v31, v2
	v_mov_b32_e32 v32, v2
	v_mov_b32_e32 v33, v2
	v_mov_b32_e32 v34, v2
	v_mov_b32_e32 v35, v2
	v_mov_b32_e32 v36, v2
	v_mov_b32_e32 v37, v2
	v_mov_b32_e32 v38, v2
	v_mov_b32_e32 v39, v2
	v_mov_b32_e32 v40, v2
	v_mov_b32_e32 v41, v2
	v_mov_b32_e32 v42, v2
	v_mov_b32_e32 v43, v2
	v_mov_b32_e32 v44, v2
	v_mov_b32_e32 v45, v2
	v_mov_b32_e32 v46, v2
	v_mov_b32_e32 v47, v2
	v_mov_b32_e32 v48, v2
	v_mov_b32_e32 v49, v2
	v_mov_b32_e32 v50, v2
	v_mov_b32_e32 v51, v2
	v_mov_b32_e32 v52, v2
	v_mov_b32_e32 v53, v2
	v_mov_b32_e32 v54, v2
	v_mov_b32_e32 v55, v2
	v_mov_b32_e32 v56, v2
	v_mov_b32_e32 v57, v2
	v_mov_b32_e32 v58, v2
	v_mov_b32_e32 v59, v2
	v_mov_b32_e32 v60, v2
	v_mov_b32_e32 v61, v2
	v_mov_b32_e32 v62, v2
	v_mov_b32_e32 v63, v2
	v_mov_b32_e32 v64, v2
	v_mov_b32_e32 v65, v2
	v_mov_b32_e32 v66, v2
	v_mov_b32_e32 v67, v2
	v_mov_b32_e32 v68, v2
	v_mov_b32_e32 v69, v2
	v_mov_b32_e32 v70, v2
	v_mov_b32_e32 v71, v2
	v_mov_b32_e32 v72, v2
	v_mov_b32_e32 v73, v2
	v_mov_b32_e32 v74, v2
	v_mov_b32_e32 v75, v2
	v_mov_b32_e32 v76, v2
	v_mov_b32_e32 v77, v2
	v_mov_b32_e32 v78, v2
	v_mov_b32_e32 v79, v2
	v_mov_b32_e32 v80, v2
	v_mov_b32_e32 v81, v2
	v_mov_b32_e32 v82, v2
	v_mov_b32_e32 v83, v2
	v_mov_b32_e32 v84, v2
	v_mov_b32_e32 v85, v2
	v_mov_b32_e32 v86, v2
	v_mov_b32_e32 v87, v2
	v_mov_b32_e32 v88, v2
	v_mov_b32_e32 v89, v2
	v_mov_b32_e32 v90, v2
	v_mov_b32_e32 v91, v2
	v_mov_b32_e32 v92, v2
	v_mov_b32_e32 v93, v2
	v_mov_b32_e32 v94, v2
	v_mov_b32_e32 v95, v2
	v_mov_b32_e32 v96, v2
	v_mov_b32_e32 v97, v2
	s_waitcnt lgkmcnt(0)
	s_barrier
	v_readfirstlane_b32 s4, v137
	v_lshrrev_b32_e32 v172, 6, v203
	s_nop 0
	v_readfirstlane_b32 s12, v172
	v_and_b32_e32 v172, 63, v203
	v_lshrrev_b32_e32 v173, 6, v203
	v_and_b32_e32 v174, 15, v172
	v_lshrrev_b32_e32 v175, 4, v172
	v_bfe_u32 v176, v172, 1, 3
	v_xor_b32_e32 v177, v175, v176
	v_lshlrev_b32_e32 v177, 4, v177
	v_or_b32_e32 v175, 4, v175
	v_xor_b32_e32 v175, v175, v176
	v_lshlrev_b32_e32 v175, 4, v175
	v_lshrrev_b32_e32 v176, 2, v173
	v_and_b32_e32 v173, 3, v173
	v_mul_u32_u24_e32 v176, 0x60, v176
	v_add_u32_e32 v176, v176, v174
	v_lshlrev_b32_e32 v176, 7, v176
	v_lshl_add_u32 v173, v173, 6, v174
	v_lshlrev_b32_e32 v173, 7, v173
	v_add_u32_e32 v173, 0x6020, v173
	v_add_u32_e32 v176, 32, v176
	v_add_u32_e32 v204, v176, v177
	v_add_u32_e32 v205, v176, v175
	v_add_u32_e32 v206, v173, v177
	v_add_u32_e32 v207, v173, v175
	s_cmp_ge_u32 s34, s84
	s_cbranch_scc1 .Lgk_last
.Lgk_main:
	s_bitcmp1_b32 s34, 0
	s_cselect_b32 s21, 0, 0xec00
	s_cselect_b32 s5, 0xec00, 0
	s_add_i32 s5, s5, s4
	s_cmp_lt_u32 s12, 4
	s_cbranch_scc0 .Lgk_nl
	s_mov_b32 m0, s5
	v_lshl_add_u64 v[176:177], v[100:101], 0, s[2:3]
	global_load_lds_dwordx4 v[176:177], off
	s_add_i32 m0, s5, 0x1000
	v_lshl_add_u64 v[176:177], v[176:177], 0, s[8:9]
	global_load_lds_dwordx4 v[176:177], off
	s_add_i32 m0, s5, 0x2000
	v_lshl_add_u64 v[176:177], v[104:105], 0, s[2:3]
	global_load_lds_dwordx4 v[176:177], off
	s_add_i32 m0, s5, 0x3000
	v_lshl_add_u64 v[176:177], v[176:177], 0, s[8:9]
	global_load_lds_dwordx4 v[176:177], off
	s_add_i32 m0, s5, 0x4000
	v_lshl_add_u64 v[176:177], v[102:103], 0, s[2:3]
	global_load_lds_dwordx4 v[176:177], off
	s_add_i32 m0, s5, 0x5000
	v_lshl_add_u64 v[176:177], v[176:177], 0, s[8:9]
	global_load_lds_dwordx4 v[176:177], off
	s_add_i32 m0, s5, 0x6000
	v_lshl_add_u64 v[176:177], v[106:107], 0, s[2:3]
	global_load_lds_dwordx4 v[176:177], off
	s_add_i32 m0, s5, 0x7000
	v_lshl_add_u64 v[176:177], v[176:177], 0, s[10:11]
	global_load_lds_dwordx4 v[176:177], off
	s_add_i32 m0, s5, 0x8000
	v_lshl_add_u64 v[176:177], v[112:113], 0, s[2:3]
	global_load_lds_dwordx4 v[176:177], off
	s_add_i32 m0, s5, 0x9000
	v_lshl_add_u64 v[176:177], v[176:177], 0, s[10:11]
	global_load_lds_dwordx4 v[176:177], off
	s_add_i32 m0, s5, 0xa000
	v_lshl_add_u64 v[176:177], v[108:109], 0, s[2:3]
	global_load_lds_dwordx4 v[176:177], off
	s_add_i32 m0, s5, 0xb000
	v_lshl_add_u64 v[176:177], v[176:177], 0, s[10:11]
	global_load_lds_dwordx4 v[176:177], off
	s_add_i32 m0, s5, 0xc000
	v_lshl_add_u64 v[176:177], v[110:111], 0, s[2:3]
	global_load_lds_dwordx4 v[176:177], off
	s_add_i32 m0, s5, 0xd000
	v_lshl_add_u64 v[176:177], v[176:177], 0, s[10:11]
	global_load_lds_dwordx4 v[176:177], off
.Lgk_nl:
	v_add_u32_e32 v172, s21, v204
	v_add_u32_e32 v173, s21, v206
	v_add_u32_e32 v174, s21, v205
	v_add_u32_e32 v175, s21, v207
	ds_read_b128 v[208:211], v173
	ds_read_b128 v[212:215], v173 offset:2048
	ds_read_b128 v[216:219], v173 offset:4096
	ds_read_b128 v[220:223], v173 offset:6144
	ds_read_b128 v[148:151], v172
	ds_read_b128 v[152:155], v172 offset:2048
	ds_read_b128 v[156:159], v172 offset:4096
	ds_read_b128 v[160:163], v172 offset:6144
	ds_read_b128 v[164:167], v172 offset:8192
	ds_read_b128 v[168:171], v172 offset:10240
	s_waitcnt lgkmcnt(5)
	v_mfma_f32_16x16x32_bf16 v[82:85], v[148:151], v[208:211], v[82:85]
	v_mfma_f32_16x16x32_bf16 v[86:89], v[148:151], v[212:215], v[86:89]
	v_mfma_f32_16x16x32_bf16 v[66:69], v[148:151], v[216:219], v[66:69]
	v_mfma_f32_16x16x32_bf16 v[70:73], v[148:151], v[220:223], v[70:73]
	ds_read_b128 v[148:151], v174
	ds_read_b128 v[224:227], v175
	ds_read_b128 v[228:231], v175 offset:2048
	ds_read_b128 v[232:235], v175 offset:4096
	ds_read_b128 v[236:239], v175 offset:6144
	s_waitcnt lgkmcnt(9)
	v_mfma_f32_16x16x32_bf16 v[90:93], v[152:155], v[208:211], v[90:93]
	v_mfma_f32_16x16x32_bf16 v[94:97], v[152:155], v[212:215], v[94:97]
	v_mfma_f32_16x16x32_bf16 v[74:77], v[152:155], v[216:219], v[74:77]
	v_mfma_f32_16x16x32_bf16 v[78:81], v[152:155], v[220:223], v[78:81]
	ds_read_b128 v[152:155], v174 offset:2048
	s_waitcnt lgkmcnt(9)
	v_mfma_f32_16x16x32_bf16 v[50:53], v[156:159], v[208:211], v[50:53]
	v_mfma_f32_16x16x32_bf16 v[54:57], v[156:159], v[212:215], v[54:57]
	v_mfma_f32_16x16x32_bf16 v[34:37], v[156:159], v[216:219], v[34:37]
	v_mfma_f32_16x16x32_bf16 v[38:41], v[156:159], v[220:223], v[38:41]
	ds_read_b128 v[156:159], v174 offset:4096
	s_waitcnt lgkmcnt(9)
	v_mfma_f32_16x16x32_bf16 v[58:61], v[160:163], v[208:211], v[58:61]
	v_mfma_f32_16x16x32_bf16 v[62:65], v[160:163], v[212:215], v[62:65]
	v_mfma_f32_16x16x32_bf16 v[42:45], v[160:163], v[216:219], v[42:45]
	v_mfma_f32_16x16x32_bf16 v[46:49], v[160:163], v[220:223], v[46:49]
	ds_read_b128 v[160:163], v174 offset:6144
	s_waitcnt lgkmcnt(9)
	v_mfma_f32_16x16x32_bf16 v[18:21], v[164:167], v[208:211], v[18:21]
	v_mfma_f32_16x16x32_bf16 v[22:25], v[164:167], v[212:215], v[22:25]
	v_mfma_f32_16x16x32_bf16 v[2:5], v[164:167], v[216:219], v[2:5]
	v_mfma_f32_16x16x32_bf16 v[6:9], v[164:167], v[220:223], v[6:9]
	ds_read_b128 v[164:167], v174 offset:8192
	s_waitcnt lgkmcnt(9)
	v_mfma_f32_16x16x32_bf16 v[26:29], v[168:171], v[208:211], v[26:29]
	v_mfma_f32_16x16x32_bf16 v[30:33], v[168:171], v[212:215], v[30:33]
	v_mfma_f32_16x16x32_bf16 v[10:13], v[168:171], v[216:219], v[10:13]
	v_mfma_f32_16x16x32_bf16 v[14:17], v[168:171], v[220:223], v[14:17]
	ds_read_b128 v[168:171], v174 offset:10240
	s_waitcnt lgkmcnt(5)
	v_mfma_f32_16x16x32_bf16 v[82:85], v[148:151], v[224:227], v[82:85]
	v_mfma_f32_16x16x32_bf16 v[86:89], v[148:151], v[228:231], v[86:89]
	v_mfma_f32_16x16x32_bf16 v[66:69], v[148:151], v[232:235], v[66:69]
	v_mfma_f32_16x16x32_bf16 v[70:73], v[148:151], v[236:239], v[70:73]
	s_waitcnt lgkmcnt(4)
	v_mfma_f32_16x16x32_bf16 v[90:93], v[152:155], v[224:227], v[90:93]
	v_mfma_f32_16x16x32_bf16 v[94:97], v[152:155], v[228:231], v[94:97]
	v_mfma_f32_16x16x32_bf16 v[74:77], v[152:155], v[232:235], v[74:77]
	v_mfma_f32_16x16x32_bf16 v[78:81], v[152:155], v[236:239], v[78:81]
	s_waitcnt lgkmcnt(3)
	v_mfma_f32_16x16x32_bf16 v[50:53], v[156:159], v[224:227], v[50:53]
	v_mfma_f32_16x16x32_bf16 v[54:57], v[156:159], v[228:231], v[54:57]
	v_mfma_f32_16x16x32_bf16 v[34:37], v[156:159], v[232:235], v[34:37]
	v_mfma_f32_16x16x32_bf16 v[38:41], v[156:159], v[236:239], v[38:41]
	s_waitcnt lgkmcnt(2)
	v_mfma_f32_16x16x32_bf16 v[58:61], v[160:163], v[224:227], v[58:61]
	v_mfma_f32_16x16x32_bf16 v[62:65], v[160:163], v[228:231], v[62:65]
	v_mfma_f32_16x16x32_bf16 v[42:45], v[160:163], v[232:235], v[42:45]
	v_mfma_f32_16x16x32_bf16 v[46:49], v[160:163], v[236:239], v[46:49]
	s_waitcnt lgkmcnt(1)
	v_mfma_f32_16x16x32_bf16 v[18:21], v[164:167], v[224:227], v[18:21]
	v_mfma_f32_16x16x32_bf16 v[22:25], v[164:167], v[228:231], v[22:25]
	v_mfma_f32_16x16x32_bf16 v[2:5], v[164:167], v[232:235], v[2:5]
	v_mfma_f32_16x16x32_bf16 v[6:9], v[164:167], v[236:239], v[6:9]
	s_waitcnt lgkmcnt(0)
	v_mfma_f32_16x16x32_bf16 v[26:29], v[168:171], v[224:227], v[26:29]
	v_mfma_f32_16x16x32_bf16 v[30:33], v[168:171], v[228:231], v[30:33]
	v_mfma_f32_16x16x32_bf16 v[10:13], v[168:171], v[232:235], v[10:13]
	v_mfma_f32_16x16x32_bf16 v[14:17], v[168:171], v[236:239], v[14:17]
	s_add_i32 s34, s34, 1
	s_add_u32 s2, s2, 0x80
	s_addc_u32 s3, s3, 0
	s_waitcnt vmcnt(0)
	s_barrier
	s_cmp_ge_u32 s34, s84
	s_cbranch_scc0 .Lgk_main
